# all three residual-update epilogues: X loads prefetched one row ahead (counted waits) instead of 32 serialized load/store chains
# baseline (speedup 1.0000x reference)
.LBB0_1521:
	v_and_b32_e32 v140, 64, v197
	v_xor_b32_e32 v139, 16, v197
	v_add_u32_e32 v140, 64, v140
	v_cmp_lt_i32_e32 vcc, v139, v140
	v_lshl_add_u32 v138, s48, 8, v142
	v_lshl_or_b32 v136, s47, 8, v144
	v_cndmask_b32_e32 v139, v197, v139, vcc
	v_lshlrev_b32_e32 v162, 2, v139
	v_xor_b32_e32 v139, 32, v197
	v_cmp_lt_i32_e32 vcc, v139, v140
	v_ashrrev_i32_e32 v137, 31, v136
	s_lshl_b32 s24, s47, 2
	v_cndmask_b32_e32 v139, v197, v139, vcc
	v_lshlrev_b32_e32 v160, 2, v139
	v_ashrrev_i32_e32 v139, 31, v138
	v_lshlrev_b64 v[140:141], 10, v[138:139]
	v_lshl_add_u64 v[168:169], v[140:141], 0, v[136:137]
	v_lshl_add_u64 v[140:141], v[168:169], 2, s[4:5]
	v_mov_b64_e32 v[204:205], v[140:141]
	global_load_dwordx4 v[208:211], v[204:205], off
	global_load_dwordx4 v[212:215], v[204:205], off offset:64
	global_load_dwordx4 v[216:219], v[204:205], off offset:512
	global_load_dwordx4 v[220:223], v[204:205], off offset:576
	s_mov_b64 s[26:27], 0x10000
	v_lshl_add_u64 v[206:207], v[204:205], 0, s[26:27]
	global_load_dwordx4 v[224:227], v[206:207], off
	global_load_dwordx4 v[228:231], v[206:207], off offset:64
	global_load_dwordx4 v[232:235], v[206:207], off offset:512
	global_load_dwordx4 v[236:239], v[206:207], off offset:576
	s_ashr_i32 s25, s24, 31
	s_waitcnt vmcnt(7)
	v_mov_b64_e32 v[164:165], v[208:209]
	v_mov_b64_e32 v[166:167], v[210:211]
	v_pk_add_f32 v[166:167], v[128:129], v[166:167]
	v_pk_add_f32 v[164:165], v[126:127], v[164:165]
	v_lshlrev_b64 v[126:127], 1, v[168:169]
	v_cvt_pk_bf16_f32 v128, v164, v165
	v_cvt_pk_bf16_f32 v129, v166, v167
	v_lshl_add_u64 v[168:169], s[12:13], 0, v[126:127]
	global_store_dwordx4 v[140:141], v[164:167], off
	global_store_dwordx2 v[168:169], v[128:129], off
	v_mul_f32_e32 v128, v165, v165
	v_mul_f32_e32 v129, v167, v167
	v_fmac_f32_e32 v128, v164, v164
	v_fmac_f32_e32 v129, v166, v166
	v_add_f32_e32 v163, v128, v129
	s_waitcnt vmcnt(8)
	v_mov_b64_e32 v[164:165], v[212:213]
	v_mov_b64_e32 v[166:167], v[214:215]
	v_pk_add_f32 v[124:125], v[124:125], v[166:167]
	v_pk_add_f32 v[122:123], v[122:123], v[164:165]
	global_store_dwordx4 v[140:141], v[122:125], off offset:64
	v_cvt_pk_bf16_f32 v128, v122, v123
	v_or_b32_e32 v164, 32, v126
	v_mul_f32_e32 v123, v123, v123
	v_mov_b32_e32 v165, v127
	v_fmac_f32_e32 v123, v122, v122
	v_mul_f32_e32 v122, v125, v125
	v_cvt_pk_bf16_f32 v129, v124, v125
	v_lshl_add_u64 v[164:165], s[12:13], 0, v[164:165]
	v_fmac_f32_e32 v122, v124, v124
	global_store_dwordx2 v[164:165], v[128:129], off
	v_add_f32_e32 v122, v123, v122
	v_add_f32_e32 v128, v163, v122
	s_waitcnt vmcnt(9)
	v_mov_b64_e32 v[122:123], v[216:217]
	v_mov_b64_e32 v[124:125], v[218:219]
	v_pk_add_f32 v[120:121], v[120:121], v[124:125]
	v_pk_add_f32 v[118:119], v[118:119], v[122:123]
	global_store_dwordx4 v[140:141], v[118:121], off offset:512
	v_cvt_pk_bf16_f32 v122, v118, v119
	v_or_b32_e32 v124, 0x100, v126
	v_mul_f32_e32 v119, v119, v119
	v_mov_b32_e32 v125, v127
	v_fmac_f32_e32 v119, v118, v118
	v_mul_f32_e32 v118, v121, v121
	v_cvt_pk_bf16_f32 v123, v120, v121
	v_lshl_add_u64 v[124:125], s[12:13], 0, v[124:125]
	v_fmac_f32_e32 v118, v120, v120
	global_store_dwordx2 v[124:125], v[122:123], off
	v_add_f32_e32 v118, v119, v118
	v_add_f32_e32 v122, v128, v118
	v_or_b32_e32 v126, 0x120, v126
	s_waitcnt vmcnt(10)
	v_mov_b64_e32 v[118:119], v[220:221]
	v_mov_b64_e32 v[120:121], v[222:223]
	v_pk_add_f32 v[116:117], v[116:117], v[120:121]
	v_pk_add_f32 v[114:115], v[114:115], v[118:119]
	global_store_dwordx4 v[140:141], v[114:117], off offset:576
	v_cvt_pk_bf16_f32 v118, v114, v115
	v_cvt_pk_bf16_f32 v119, v116, v117
	v_mul_f32_e32 v115, v115, v115
	v_fmac_f32_e32 v115, v114, v114
	v_mul_f32_e32 v114, v117, v117
	v_fmac_f32_e32 v114, v116, v116
	v_add_f32_e32 v114, v115, v114
	v_add_f32_e32 v114, v122, v114
	ds_bpermute_b32 v115, v162, v114
	v_lshl_add_u64 v[120:121], s[12:13], 0, v[126:127]
	global_store_dwordx2 v[120:121], v[118:119], off
	s_waitcnt lgkmcnt(0)
	v_add_f32_e32 v114, v114, v115
	ds_bpermute_b32 v115, v160, v114
	s_and_saveexec_b64 s[26:27], s[8:9]
	s_cbranch_execz .LBB0_1523
	v_lshlrev_b64 v[116:117], 6, v[138:139]
	v_lshl_add_u64 v[116:117], s[66:67], 0, v[116:117]
	v_lshl_add_u64 v[116:117], s[24:25], 2, v[116:117]
	s_lshl_b32 s68, s43, 2
	v_lshl_add_u64 v[116:117], v[116:117], 0, s[68:69]
	s_waitcnt lgkmcnt(0)
	v_add_f32_e32 v114, v114, v115
	global_store_dword v[116:117], v114, off
.LBB0_1523:
	s_or_b64 exec, exec, s[26:27]
	v_or_b32_e32 v114, 16, v138
	s_waitcnt lgkmcnt(0)
	v_ashrrev_i32_e32 v115, 31, v114
	v_lshlrev_b64 v[116:117], 10, v[114:115]
	v_lshl_add_u64 v[122:123], v[116:117], 0, v[136:137]
	v_lshl_add_u64 v[116:117], v[122:123], 2, s[4:5]
	s_mov_b64 s[26:27], 0x20000
	v_lshl_add_u64 v[206:207], v[204:205], 0, s[26:27]
	global_load_dwordx4 v[208:211], v[206:207], off
	global_load_dwordx4 v[212:215], v[206:207], off offset:64
	global_load_dwordx4 v[216:219], v[206:207], off offset:512
	global_load_dwordx4 v[220:223], v[206:207], off offset:576
	s_waitcnt vmcnt(16)
	v_mov_b64_e32 v[118:119], v[224:225]
	v_mov_b64_e32 v[120:121], v[226:227]
	v_pk_add_f32 v[120:121], v[112:113], v[120:121]
	v_pk_add_f32 v[118:119], v[110:111], v[118:119]
	v_lshlrev_b64 v[110:111], 1, v[122:123]
	v_cvt_pk_bf16_f32 v112, v118, v119
	v_cvt_pk_bf16_f32 v113, v120, v121
	v_lshl_add_u64 v[122:123], s[12:13], 0, v[110:111]
	global_store_dwordx4 v[116:117], v[118:121], off
	global_store_dwordx2 v[122:123], v[112:113], off
	v_mul_f32_e32 v112, v119, v119
	v_mul_f32_e32 v113, v121, v121
	v_fmac_f32_e32 v112, v118, v118
	v_fmac_f32_e32 v113, v120, v120
	v_add_f32_e32 v122, v112, v113
	s_waitcnt vmcnt(17)
	v_mov_b64_e32 v[118:119], v[228:229]
	v_mov_b64_e32 v[120:121], v[230:231]
	v_pk_add_f32 v[108:109], v[108:109], v[120:121]
	v_pk_add_f32 v[106:107], v[106:107], v[118:119]
	global_store_dwordx4 v[116:117], v[106:109], off offset:64
	v_cvt_pk_bf16_f32 v112, v106, v107
	v_or_b32_e32 v118, 32, v110
	v_mul_f32_e32 v107, v107, v107
	v_mov_b32_e32 v119, v111
	v_fmac_f32_e32 v107, v106, v106
	v_mul_f32_e32 v106, v109, v109
	v_cvt_pk_bf16_f32 v113, v108, v109
	v_lshl_add_u64 v[118:119], s[12:13], 0, v[118:119]
	v_fmac_f32_e32 v106, v108, v108
	global_store_dwordx2 v[118:119], v[112:113], off
	v_add_f32_e32 v106, v107, v106
	v_add_f32_e32 v112, v122, v106
	s_waitcnt vmcnt(18)
	v_mov_b64_e32 v[106:107], v[232:233]
	v_mov_b64_e32 v[108:109], v[234:235]
	v_pk_add_f32 v[104:105], v[104:105], v[108:109]
	v_pk_add_f32 v[102:103], v[102:103], v[106:107]
	global_store_dwordx4 v[116:117], v[102:105], off offset:512
	v_cvt_pk_bf16_f32 v106, v102, v103
	v_or_b32_e32 v108, 0x100, v110
	v_mul_f32_e32 v103, v103, v103
	v_mov_b32_e32 v109, v111
	v_fmac_f32_e32 v103, v102, v102
	v_mul_f32_e32 v102, v105, v105
	v_cvt_pk_bf16_f32 v107, v104, v105
	v_lshl_add_u64 v[108:109], s[12:13], 0, v[108:109]
	v_fmac_f32_e32 v102, v104, v104
	global_store_dwordx2 v[108:109], v[106:107], off
	v_add_f32_e32 v102, v103, v102
	v_add_f32_e32 v106, v112, v102
	v_or_b32_e32 v110, 0x120, v110
	s_waitcnt vmcnt(19)
	v_mov_b64_e32 v[102:103], v[236:237]
	v_mov_b64_e32 v[104:105], v[238:239]
	v_pk_add_f32 v[100:101], v[100:101], v[104:105]
	v_pk_add_f32 v[98:99], v[98:99], v[102:103]
	global_store_dwordx4 v[116:117], v[98:101], off offset:576
	v_cvt_pk_bf16_f32 v102, v98, v99
	v_cvt_pk_bf16_f32 v103, v100, v101
	v_mul_f32_e32 v99, v99, v99
	v_fmac_f32_e32 v99, v98, v98
	v_mul_f32_e32 v98, v101, v101
	v_fmac_f32_e32 v98, v100, v100
	v_add_f32_e32 v98, v99, v98
	v_add_f32_e32 v98, v106, v98
	ds_bpermute_b32 v99, v162, v98
	v_lshl_add_u64 v[104:105], s[12:13], 0, v[110:111]
	global_store_dwordx2 v[104:105], v[102:103], off
	s_waitcnt lgkmcnt(0)
	v_add_f32_e32 v98, v98, v99
	ds_bpermute_b32 v99, v160, v98
	s_and_saveexec_b64 s[26:27], s[8:9]
	s_cbranch_execz .LBB0_1525
	v_lshlrev_b64 v[100:101], 6, v[114:115]
	v_lshl_add_u64 v[100:101], s[66:67], 0, v[100:101]
	v_lshl_add_u64 v[100:101], s[24:25], 2, v[100:101]
	s_lshl_b32 s68, s43, 2
	v_lshl_add_u64 v[100:101], v[100:101], 0, s[68:69]
	s_waitcnt lgkmcnt(0)
	v_add_f32_e32 v98, v98, v99
	global_store_dword v[100:101], v98, off
.LBB0_1525:
	s_or_b64 exec, exec, s[26:27]
	v_or_b32_e32 v98, 32, v138
	s_waitcnt lgkmcnt(0)
	v_ashrrev_i32_e32 v99, 31, v98
	v_lshlrev_b64 v[100:101], 10, v[98:99]
	v_lshl_add_u64 v[106:107], v[100:101], 0, v[136:137]
	v_lshl_add_u64 v[100:101], v[106:107], 2, s[4:5]
	s_mov_b64 s[26:27], 0x30000
	v_lshl_add_u64 v[206:207], v[204:205], 0, s[26:27]
	global_load_dwordx4 v[224:227], v[206:207], off
	global_load_dwordx4 v[228:231], v[206:207], off offset:64
	global_load_dwordx4 v[232:235], v[206:207], off offset:512
	global_load_dwordx4 v[236:239], v[206:207], off offset:576
	s_waitcnt vmcnt(16)
	v_mov_b64_e32 v[102:103], v[208:209]
	v_mov_b64_e32 v[104:105], v[210:211]
	v_pk_add_f32 v[104:105], v[96:97], v[104:105]
	v_pk_add_f32 v[102:103], v[94:95], v[102:103]
	v_lshlrev_b64 v[94:95], 1, v[106:107]
	v_cvt_pk_bf16_f32 v96, v102, v103
	v_cvt_pk_bf16_f32 v97, v104, v105
	v_lshl_add_u64 v[106:107], s[12:13], 0, v[94:95]
	global_store_dwordx4 v[100:101], v[102:105], off
	global_store_dwordx2 v[106:107], v[96:97], off
	v_mul_f32_e32 v96, v103, v103
	v_mul_f32_e32 v97, v105, v105
	v_fmac_f32_e32 v96, v102, v102
	v_fmac_f32_e32 v97, v104, v104
	v_add_f32_e32 v106, v96, v97
	s_waitcnt vmcnt(17)
	v_mov_b64_e32 v[102:103], v[212:213]
	v_mov_b64_e32 v[104:105], v[214:215]
	v_pk_add_f32 v[92:93], v[92:93], v[104:105]
	v_pk_add_f32 v[90:91], v[90:91], v[102:103]
	global_store_dwordx4 v[100:101], v[90:93], off offset:64
	v_cvt_pk_bf16_f32 v96, v90, v91
	v_or_b32_e32 v102, 32, v94
	v_mul_f32_e32 v91, v91, v91
	v_mov_b32_e32 v103, v95
	v_fmac_f32_e32 v91, v90, v90
	v_mul_f32_e32 v90, v93, v93
	v_cvt_pk_bf16_f32 v97, v92, v93
	v_lshl_add_u64 v[102:103], s[12:13], 0, v[102:103]
	v_fmac_f32_e32 v90, v92, v92
	global_store_dwordx2 v[102:103], v[96:97], off
	v_add_f32_e32 v90, v91, v90
	v_add_f32_e32 v96, v106, v90
	s_waitcnt vmcnt(18)
	v_mov_b64_e32 v[90:91], v[216:217]
	v_mov_b64_e32 v[92:93], v[218:219]
	v_pk_add_f32 v[88:89], v[88:89], v[92:93]
	v_pk_add_f32 v[86:87], v[86:87], v[90:91]
	global_store_dwordx4 v[100:101], v[86:89], off offset:512
	v_cvt_pk_bf16_f32 v90, v86, v87
	v_or_b32_e32 v92, 0x100, v94
	v_mul_f32_e32 v87, v87, v87
	v_mov_b32_e32 v93, v95
	v_fmac_f32_e32 v87, v86, v86
	v_mul_f32_e32 v86, v89, v89
	v_cvt_pk_bf16_f32 v91, v88, v89
	v_lshl_add_u64 v[92:93], s[12:13], 0, v[92:93]
	v_fmac_f32_e32 v86, v88, v88
	global_store_dwordx2 v[92:93], v[90:91], off
	v_add_f32_e32 v86, v87, v86
	v_add_f32_e32 v90, v96, v86
	v_or_b32_e32 v94, 0x120, v94
	s_waitcnt vmcnt(19)
	v_mov_b64_e32 v[86:87], v[220:221]
	v_mov_b64_e32 v[88:89], v[222:223]
	v_pk_add_f32 v[84:85], v[84:85], v[88:89]
	v_pk_add_f32 v[82:83], v[82:83], v[86:87]
	global_store_dwordx4 v[100:101], v[82:85], off offset:576
	v_cvt_pk_bf16_f32 v86, v82, v83
	v_cvt_pk_bf16_f32 v87, v84, v85
	v_mul_f32_e32 v83, v83, v83
	v_fmac_f32_e32 v83, v82, v82
	v_mul_f32_e32 v82, v85, v85
	v_fmac_f32_e32 v82, v84, v84
	v_add_f32_e32 v82, v83, v82
	v_add_f32_e32 v82, v90, v82
	ds_bpermute_b32 v83, v162, v82
	v_lshl_add_u64 v[88:89], s[12:13], 0, v[94:95]
	global_store_dwordx2 v[88:89], v[86:87], off
	s_waitcnt lgkmcnt(0)
	v_add_f32_e32 v82, v82, v83
	ds_bpermute_b32 v83, v160, v82
	s_and_saveexec_b64 s[26:27], s[8:9]
	s_cbranch_execz .LBB0_1527
	v_lshlrev_b64 v[84:85], 6, v[98:99]
	v_lshl_add_u64 v[84:85], s[66:67], 0, v[84:85]
	v_lshl_add_u64 v[84:85], s[24:25], 2, v[84:85]
	s_lshl_b32 s68, s43, 2
	v_lshl_add_u64 v[84:85], v[84:85], 0, s[68:69]
	s_waitcnt lgkmcnt(0)
	v_add_f32_e32 v82, v82, v83
	global_store_dword v[84:85], v82, off
.LBB0_1527:
	s_or_b64 exec, exec, s[26:27]
	v_or_b32_e32 v82, 48, v138
	s_waitcnt lgkmcnt(0)
	v_ashrrev_i32_e32 v83, 31, v82
	v_lshlrev_b64 v[84:85], 10, v[82:83]
	v_lshl_add_u64 v[90:91], v[84:85], 0, v[136:137]
	v_lshl_add_u64 v[84:85], v[90:91], 2, s[4:5]
	s_mov_b64 s[26:27], 0x80000
	v_lshl_add_u64 v[206:207], v[204:205], 0, s[26:27]
	global_load_dwordx4 v[208:211], v[206:207], off
	global_load_dwordx4 v[212:215], v[206:207], off offset:64
	global_load_dwordx4 v[216:219], v[206:207], off offset:512
	global_load_dwordx4 v[220:223], v[206:207], off offset:576
	s_waitcnt vmcnt(16)
	v_mov_b64_e32 v[86:87], v[224:225]
	v_mov_b64_e32 v[88:89], v[226:227]
	v_pk_add_f32 v[88:89], v[80:81], v[88:89]
	v_pk_add_f32 v[86:87], v[78:79], v[86:87]
	v_lshlrev_b64 v[78:79], 1, v[90:91]
	v_cvt_pk_bf16_f32 v80, v86, v87
	v_cvt_pk_bf16_f32 v81, v88, v89
	v_lshl_add_u64 v[90:91], s[12:13], 0, v[78:79]
	global_store_dwordx4 v[84:85], v[86:89], off
	global_store_dwordx2 v[90:91], v[80:81], off
	v_mul_f32_e32 v80, v87, v87
	v_mul_f32_e32 v81, v89, v89
	v_fmac_f32_e32 v80, v86, v86
	v_fmac_f32_e32 v81, v88, v88
	v_add_f32_e32 v90, v80, v81
	s_waitcnt vmcnt(17)
	v_mov_b64_e32 v[86:87], v[228:229]
	v_mov_b64_e32 v[88:89], v[230:231]
	v_pk_add_f32 v[76:77], v[76:77], v[88:89]
	v_pk_add_f32 v[74:75], v[74:75], v[86:87]
	global_store_dwordx4 v[84:85], v[74:77], off offset:64
	v_cvt_pk_bf16_f32 v80, v74, v75
	v_or_b32_e32 v86, 32, v78
	v_mul_f32_e32 v75, v75, v75
	v_mov_b32_e32 v87, v79
	v_fmac_f32_e32 v75, v74, v74
	v_mul_f32_e32 v74, v77, v77
	v_cvt_pk_bf16_f32 v81, v76, v77
	v_lshl_add_u64 v[86:87], s[12:13], 0, v[86:87]
	v_fmac_f32_e32 v74, v76, v76
	global_store_dwordx2 v[86:87], v[80:81], off
	v_add_f32_e32 v74, v75, v74
	v_add_f32_e32 v80, v90, v74
	s_waitcnt vmcnt(18)
	v_mov_b64_e32 v[74:75], v[232:233]
	v_mov_b64_e32 v[76:77], v[234:235]
	v_pk_add_f32 v[72:73], v[72:73], v[76:77]
	v_pk_add_f32 v[70:71], v[70:71], v[74:75]
	global_store_dwordx4 v[84:85], v[70:73], off offset:512
	v_cvt_pk_bf16_f32 v74, v70, v71
	v_or_b32_e32 v76, 0x100, v78
	v_mul_f32_e32 v71, v71, v71
	v_mov_b32_e32 v77, v79
	v_fmac_f32_e32 v71, v70, v70
	v_mul_f32_e32 v70, v73, v73
	v_cvt_pk_bf16_f32 v75, v72, v73
	v_lshl_add_u64 v[76:77], s[12:13], 0, v[76:77]
	v_fmac_f32_e32 v70, v72, v72
	global_store_dwordx2 v[76:77], v[74:75], off
	v_add_f32_e32 v70, v71, v70
	v_add_f32_e32 v74, v80, v70
	v_or_b32_e32 v78, 0x120, v78
	s_waitcnt vmcnt(19)
	v_mov_b64_e32 v[70:71], v[236:237]
	v_mov_b64_e32 v[72:73], v[238:239]
	v_pk_add_f32 v[68:69], v[68:69], v[72:73]
	v_pk_add_f32 v[66:67], v[66:67], v[70:71]
	global_store_dwordx4 v[84:85], v[66:69], off offset:576
	v_cvt_pk_bf16_f32 v70, v66, v67
	v_cvt_pk_bf16_f32 v71, v68, v69
	v_mul_f32_e32 v67, v67, v67
	v_fmac_f32_e32 v67, v66, v66
	v_mul_f32_e32 v66, v69, v69
	v_fmac_f32_e32 v66, v68, v68
	v_add_f32_e32 v66, v67, v66
	v_add_f32_e32 v66, v74, v66
	ds_bpermute_b32 v67, v162, v66
	v_lshl_add_u64 v[72:73], s[12:13], 0, v[78:79]
	global_store_dwordx2 v[72:73], v[70:71], off
	s_waitcnt lgkmcnt(0)
	v_add_f32_e32 v66, v66, v67
	ds_bpermute_b32 v67, v160, v66
	s_and_saveexec_b64 s[26:27], s[8:9]
	s_cbranch_execz .LBB0_1529
	v_lshlrev_b64 v[68:69], 6, v[82:83]
	v_lshl_add_u64 v[68:69], s[66:67], 0, v[68:69]
	v_lshl_add_u64 v[68:69], s[24:25], 2, v[68:69]
	s_lshl_b32 s68, s43, 2
	v_lshl_add_u64 v[68:69], v[68:69], 0, s[68:69]
	s_waitcnt lgkmcnt(0)
	v_add_f32_e32 v66, v66, v67
	global_store_dword v[68:69], v66, off
.LBB0_1529:
	s_or_b64 exec, exec, s[26:27]
	v_add_u32_e32 v66, 0x80, v138
	s_waitcnt lgkmcnt(0)
	v_ashrrev_i32_e32 v67, 31, v66
	v_lshlrev_b64 v[68:69], 10, v[66:67]
	v_lshl_add_u64 v[74:75], v[68:69], 0, v[136:137]
	v_lshl_add_u64 v[68:69], v[74:75], 2, s[4:5]
	s_mov_b64 s[26:27], 0x90000
	v_lshl_add_u64 v[206:207], v[204:205], 0, s[26:27]
	global_load_dwordx4 v[224:227], v[206:207], off
	global_load_dwordx4 v[228:231], v[206:207], off offset:64
	global_load_dwordx4 v[232:235], v[206:207], off offset:512
	global_load_dwordx4 v[236:239], v[206:207], off offset:576
	s_waitcnt vmcnt(16)
	v_mov_b64_e32 v[70:71], v[208:209]
	v_mov_b64_e32 v[72:73], v[210:211]
	v_pk_add_f32 v[72:73], v[64:65], v[72:73]
	v_pk_add_f32 v[70:71], v[62:63], v[70:71]
	v_lshlrev_b64 v[62:63], 1, v[74:75]
	v_cvt_pk_bf16_f32 v64, v70, v71
	v_cvt_pk_bf16_f32 v65, v72, v73
	v_lshl_add_u64 v[74:75], s[12:13], 0, v[62:63]
	global_store_dwordx4 v[68:69], v[70:73], off
	global_store_dwordx2 v[74:75], v[64:65], off
	v_mul_f32_e32 v64, v71, v71
	v_mul_f32_e32 v65, v73, v73
	v_fmac_f32_e32 v64, v70, v70
	v_fmac_f32_e32 v65, v72, v72
	v_add_f32_e32 v74, v64, v65
	s_waitcnt vmcnt(17)
	v_mov_b64_e32 v[70:71], v[212:213]
	v_mov_b64_e32 v[72:73], v[214:215]
	v_pk_add_f32 v[60:61], v[60:61], v[72:73]
	v_pk_add_f32 v[58:59], v[58:59], v[70:71]
	global_store_dwordx4 v[68:69], v[58:61], off offset:64
	v_cvt_pk_bf16_f32 v64, v58, v59
	v_or_b32_e32 v70, 32, v62
	v_mul_f32_e32 v59, v59, v59
	v_mov_b32_e32 v71, v63
	v_fmac_f32_e32 v59, v58, v58
	v_mul_f32_e32 v58, v61, v61
	v_cvt_pk_bf16_f32 v65, v60, v61
	v_lshl_add_u64 v[70:71], s[12:13], 0, v[70:71]
	v_fmac_f32_e32 v58, v60, v60
	global_store_dwordx2 v[70:71], v[64:65], off
	v_add_f32_e32 v58, v59, v58
	v_add_f32_e32 v64, v74, v58
	s_waitcnt vmcnt(18)
	v_mov_b64_e32 v[58:59], v[216:217]
	v_mov_b64_e32 v[60:61], v[218:219]
	v_pk_add_f32 v[56:57], v[56:57], v[60:61]
	v_pk_add_f32 v[54:55], v[54:55], v[58:59]
	global_store_dwordx4 v[68:69], v[54:57], off offset:512
	v_cvt_pk_bf16_f32 v58, v54, v55
	v_or_b32_e32 v60, 0x100, v62
	v_mul_f32_e32 v55, v55, v55
	v_mov_b32_e32 v61, v63
	v_fmac_f32_e32 v55, v54, v54
	v_mul_f32_e32 v54, v57, v57
	v_cvt_pk_bf16_f32 v59, v56, v57
	v_lshl_add_u64 v[60:61], s[12:13], 0, v[60:61]
	v_fmac_f32_e32 v54, v56, v56
	global_store_dwordx2 v[60:61], v[58:59], off
	v_add_f32_e32 v54, v55, v54
	v_add_f32_e32 v58, v64, v54
	v_or_b32_e32 v62, 0x120, v62
	s_waitcnt vmcnt(19)
	v_mov_b64_e32 v[54:55], v[220:221]
	v_mov_b64_e32 v[56:57], v[222:223]
	v_pk_add_f32 v[52:53], v[52:53], v[56:57]
	v_pk_add_f32 v[50:51], v[50:51], v[54:55]
	global_store_dwordx4 v[68:69], v[50:53], off offset:576
	v_cvt_pk_bf16_f32 v54, v50, v51
	v_cvt_pk_bf16_f32 v55, v52, v53
	v_mul_f32_e32 v51, v51, v51
	v_fmac_f32_e32 v51, v50, v50
	v_mul_f32_e32 v50, v53, v53
	v_fmac_f32_e32 v50, v52, v52
	v_add_f32_e32 v50, v51, v50
	v_add_f32_e32 v50, v58, v50
	ds_bpermute_b32 v51, v162, v50
	v_lshl_add_u64 v[56:57], s[12:13], 0, v[62:63]
	global_store_dwordx2 v[56:57], v[54:55], off
	s_waitcnt lgkmcnt(0)
	v_add_f32_e32 v50, v50, v51
	ds_bpermute_b32 v51, v160, v50
	s_and_saveexec_b64 s[26:27], s[8:9]
	s_cbranch_execz .LBB0_1531
	v_lshlrev_b64 v[52:53], 6, v[66:67]
	v_lshl_add_u64 v[52:53], s[66:67], 0, v[52:53]
	v_lshl_add_u64 v[52:53], s[24:25], 2, v[52:53]
	s_lshl_b32 s68, s43, 2
	v_lshl_add_u64 v[52:53], v[52:53], 0, s[68:69]
	s_waitcnt lgkmcnt(0)
	v_add_f32_e32 v50, v50, v51
	global_store_dword v[52:53], v50, off
.LBB0_1531:
	s_or_b64 exec, exec, s[26:27]
	v_add_u32_e32 v50, 0x90, v138
	s_waitcnt lgkmcnt(0)
	v_ashrrev_i32_e32 v51, 31, v50
	v_lshlrev_b64 v[52:53], 10, v[50:51]
	v_lshl_add_u64 v[58:59], v[52:53], 0, v[136:137]
	v_lshl_add_u64 v[52:53], v[58:59], 2, s[4:5]
	s_mov_b64 s[26:27], 0xa0000
	v_lshl_add_u64 v[206:207], v[204:205], 0, s[26:27]
	global_load_dwordx4 v[208:211], v[206:207], off
	global_load_dwordx4 v[212:215], v[206:207], off offset:64
	global_load_dwordx4 v[216:219], v[206:207], off offset:512
	global_load_dwordx4 v[220:223], v[206:207], off offset:576
	s_waitcnt vmcnt(16)
	v_mov_b64_e32 v[54:55], v[224:225]
	v_mov_b64_e32 v[56:57], v[226:227]
	v_pk_add_f32 v[56:57], v[48:49], v[56:57]
	v_pk_add_f32 v[54:55], v[46:47], v[54:55]
	v_lshlrev_b64 v[46:47], 1, v[58:59]
	v_cvt_pk_bf16_f32 v48, v54, v55
	v_cvt_pk_bf16_f32 v49, v56, v57
	v_lshl_add_u64 v[58:59], s[12:13], 0, v[46:47]
	global_store_dwordx4 v[52:53], v[54:57], off
	global_store_dwordx2 v[58:59], v[48:49], off
	v_mul_f32_e32 v48, v55, v55
	v_mul_f32_e32 v49, v57, v57
	v_fmac_f32_e32 v48, v54, v54
	v_fmac_f32_e32 v49, v56, v56
	v_add_f32_e32 v58, v48, v49
	s_waitcnt vmcnt(17)
	v_mov_b64_e32 v[54:55], v[228:229]
	v_mov_b64_e32 v[56:57], v[230:231]
	v_pk_add_f32 v[44:45], v[44:45], v[56:57]
	v_pk_add_f32 v[42:43], v[42:43], v[54:55]
	global_store_dwordx4 v[52:53], v[42:45], off offset:64
	v_cvt_pk_bf16_f32 v48, v42, v43
	v_or_b32_e32 v54, 32, v46
	v_mul_f32_e32 v43, v43, v43
	v_mov_b32_e32 v55, v47
	v_fmac_f32_e32 v43, v42, v42
	v_mul_f32_e32 v42, v45, v45
	v_cvt_pk_bf16_f32 v49, v44, v45
	v_lshl_add_u64 v[54:55], s[12:13], 0, v[54:55]
	v_fmac_f32_e32 v42, v44, v44
	global_store_dwordx2 v[54:55], v[48:49], off
	v_add_f32_e32 v42, v43, v42
	v_add_f32_e32 v48, v58, v42
	s_waitcnt vmcnt(18)
	v_mov_b64_e32 v[42:43], v[232:233]
	v_mov_b64_e32 v[44:45], v[234:235]
	v_pk_add_f32 v[40:41], v[40:41], v[44:45]
	v_pk_add_f32 v[38:39], v[38:39], v[42:43]
	global_store_dwordx4 v[52:53], v[38:41], off offset:512
	v_cvt_pk_bf16_f32 v42, v38, v39
	v_or_b32_e32 v44, 0x100, v46
	v_mul_f32_e32 v39, v39, v39
	v_mov_b32_e32 v45, v47
	v_fmac_f32_e32 v39, v38, v38
	v_mul_f32_e32 v38, v41, v41
	v_cvt_pk_bf16_f32 v43, v40, v41
	v_lshl_add_u64 v[44:45], s[12:13], 0, v[44:45]
	v_fmac_f32_e32 v38, v40, v40
	global_store_dwordx2 v[44:45], v[42:43], off
	v_add_f32_e32 v38, v39, v38
	v_add_f32_e32 v42, v48, v38
	v_or_b32_e32 v46, 0x120, v46
	s_waitcnt vmcnt(19)
	v_mov_b64_e32 v[38:39], v[236:237]
	v_mov_b64_e32 v[40:41], v[238:239]
	v_pk_add_f32 v[36:37], v[36:37], v[40:41]
	v_pk_add_f32 v[34:35], v[34:35], v[38:39]
	global_store_dwordx4 v[52:53], v[34:37], off offset:576
	v_cvt_pk_bf16_f32 v38, v34, v35
	v_cvt_pk_bf16_f32 v39, v36, v37
	v_mul_f32_e32 v35, v35, v35
	v_fmac_f32_e32 v35, v34, v34
	v_mul_f32_e32 v34, v37, v37
	v_fmac_f32_e32 v34, v36, v36
	v_add_f32_e32 v34, v35, v34
	v_add_f32_e32 v34, v42, v34
	ds_bpermute_b32 v35, v162, v34
	v_lshl_add_u64 v[40:41], s[12:13], 0, v[46:47]
	global_store_dwordx2 v[40:41], v[38:39], off
	s_waitcnt lgkmcnt(0)
	v_add_f32_e32 v34, v34, v35
	ds_bpermute_b32 v35, v160, v34
	s_and_saveexec_b64 s[26:27], s[8:9]
	s_cbranch_execz .LBB0_1533
	v_lshlrev_b64 v[36:37], 6, v[50:51]
	v_lshl_add_u64 v[36:37], s[66:67], 0, v[36:37]
	v_lshl_add_u64 v[36:37], s[24:25], 2, v[36:37]
	s_lshl_b32 s68, s43, 2
	v_lshl_add_u64 v[36:37], v[36:37], 0, s[68:69]
	s_waitcnt lgkmcnt(0)
	v_add_f32_e32 v34, v34, v35
	global_store_dword v[36:37], v34, off
.LBB0_1533:
	s_or_b64 exec, exec, s[26:27]
	v_add_u32_e32 v34, 0xa0, v138
	s_waitcnt lgkmcnt(0)
	v_ashrrev_i32_e32 v35, 31, v34
	v_lshlrev_b64 v[36:37], 10, v[34:35]
	v_lshl_add_u64 v[42:43], v[36:37], 0, v[136:137]
	v_lshl_add_u64 v[36:37], v[42:43], 2, s[4:5]
	s_mov_b64 s[26:27], 0xb0000
	v_lshl_add_u64 v[206:207], v[204:205], 0, s[26:27]
	global_load_dwordx4 v[224:227], v[206:207], off
	global_load_dwordx4 v[228:231], v[206:207], off offset:64
	global_load_dwordx4 v[232:235], v[206:207], off offset:512
	global_load_dwordx4 v[236:239], v[206:207], off offset:576
	s_waitcnt vmcnt(16)
	v_mov_b64_e32 v[38:39], v[208:209]
	v_mov_b64_e32 v[40:41], v[210:211]
	v_pk_add_f32 v[40:41], v[32:33], v[40:41]
	v_pk_add_f32 v[38:39], v[30:31], v[38:39]
	v_lshlrev_b64 v[30:31], 1, v[42:43]
	v_cvt_pk_bf16_f32 v32, v38, v39
	v_cvt_pk_bf16_f32 v33, v40, v41
	v_lshl_add_u64 v[42:43], s[12:13], 0, v[30:31]
	global_store_dwordx4 v[36:37], v[38:41], off
	global_store_dwordx2 v[42:43], v[32:33], off
	v_mul_f32_e32 v32, v39, v39
	v_mul_f32_e32 v33, v41, v41
	v_fmac_f32_e32 v32, v38, v38
	v_fmac_f32_e32 v33, v40, v40
	v_add_f32_e32 v42, v32, v33
	s_waitcnt vmcnt(17)
	v_mov_b64_e32 v[38:39], v[212:213]
	v_mov_b64_e32 v[40:41], v[214:215]
	v_pk_add_f32 v[28:29], v[28:29], v[40:41]
	v_pk_add_f32 v[26:27], v[26:27], v[38:39]
	global_store_dwordx4 v[36:37], v[26:29], off offset:64
	v_cvt_pk_bf16_f32 v32, v26, v27
	v_or_b32_e32 v38, 32, v30
	v_mul_f32_e32 v27, v27, v27
	v_mov_b32_e32 v39, v31
	v_fmac_f32_e32 v27, v26, v26
	v_mul_f32_e32 v26, v29, v29
	v_cvt_pk_bf16_f32 v33, v28, v29
	v_lshl_add_u64 v[38:39], s[12:13], 0, v[38:39]
	v_fmac_f32_e32 v26, v28, v28
	global_store_dwordx2 v[38:39], v[32:33], off
	v_add_f32_e32 v26, v27, v26
	v_add_f32_e32 v32, v42, v26
	s_waitcnt vmcnt(18)
	v_mov_b64_e32 v[26:27], v[216:217]
	v_mov_b64_e32 v[28:29], v[218:219]
	v_pk_add_f32 v[24:25], v[24:25], v[28:29]
	v_pk_add_f32 v[22:23], v[22:23], v[26:27]
	global_store_dwordx4 v[36:37], v[22:25], off offset:512
	v_cvt_pk_bf16_f32 v26, v22, v23
	v_or_b32_e32 v28, 0x100, v30
	v_mul_f32_e32 v23, v23, v23
	v_mov_b32_e32 v29, v31
	v_fmac_f32_e32 v23, v22, v22
	v_mul_f32_e32 v22, v25, v25
	v_cvt_pk_bf16_f32 v27, v24, v25
	v_lshl_add_u64 v[28:29], s[12:13], 0, v[28:29]
	v_fmac_f32_e32 v22, v24, v24
	global_store_dwordx2 v[28:29], v[26:27], off
	v_add_f32_e32 v22, v23, v22
	v_add_f32_e32 v26, v32, v22
	v_or_b32_e32 v30, 0x120, v30
	s_waitcnt vmcnt(19)
	v_mov_b64_e32 v[22:23], v[220:221]
	v_mov_b64_e32 v[24:25], v[222:223]
	v_pk_add_f32 v[20:21], v[20:21], v[24:25]
	v_pk_add_f32 v[18:19], v[18:19], v[22:23]
	global_store_dwordx4 v[36:37], v[18:21], off offset:576
	v_cvt_pk_bf16_f32 v22, v18, v19
	v_cvt_pk_bf16_f32 v23, v20, v21
	v_mul_f32_e32 v19, v19, v19
	v_fmac_f32_e32 v19, v18, v18
	v_mul_f32_e32 v18, v21, v21
	v_fmac_f32_e32 v18, v20, v20
	v_add_f32_e32 v18, v19, v18
	v_add_f32_e32 v18, v26, v18
	ds_bpermute_b32 v19, v162, v18
	v_lshl_add_u64 v[24:25], s[12:13], 0, v[30:31]
	global_store_dwordx2 v[24:25], v[22:23], off
	s_waitcnt lgkmcnt(0)
	v_add_f32_e32 v18, v18, v19
	ds_bpermute_b32 v19, v160, v18
	s_and_saveexec_b64 s[26:27], s[8:9]
	s_cbranch_execz .LBB0_1535
	v_lshlrev_b64 v[20:21], 6, v[34:35]
	v_lshl_add_u64 v[20:21], s[66:67], 0, v[20:21]
	v_lshl_add_u64 v[20:21], s[24:25], 2, v[20:21]
	s_lshl_b32 s68, s43, 2
	v_lshl_add_u64 v[20:21], v[20:21], 0, s[68:69]
	s_waitcnt lgkmcnt(0)
	v_add_f32_e32 v18, v18, v19
	global_store_dword v[20:21], v18, off
.LBB0_1535:
	s_or_b64 exec, exec, s[26:27]
	v_add_u32_e32 v18, 0xb0, v138
	s_waitcnt lgkmcnt(0)
	v_ashrrev_i32_e32 v19, 31, v18
	v_lshlrev_b64 v[20:21], 10, v[18:19]
	v_lshl_add_u64 v[26:27], v[20:21], 0, v[136:137]
	v_lshl_add_u64 v[20:21], v[26:27], 2, s[4:5]
	s_waitcnt vmcnt(12)
	v_mov_b64_e32 v[22:23], v[224:225]
	v_mov_b64_e32 v[24:25], v[226:227]
	v_pk_add_f32 v[24:25], v[16:17], v[24:25]
	v_pk_add_f32 v[22:23], v[14:15], v[22:23]
	v_lshlrev_b64 v[14:15], 1, v[26:27]
	v_cvt_pk_bf16_f32 v16, v22, v23
	v_cvt_pk_bf16_f32 v17, v24, v25
	v_lshl_add_u64 v[26:27], s[12:13], 0, v[14:15]
	global_store_dwordx4 v[20:21], v[22:25], off
	global_store_dwordx2 v[26:27], v[16:17], off
	v_mul_f32_e32 v16, v23, v23
	v_mul_f32_e32 v17, v25, v25
	v_fmac_f32_e32 v16, v22, v22
	v_fmac_f32_e32 v17, v24, v24
	v_add_f32_e32 v26, v16, v17
	s_waitcnt vmcnt(13)
	v_mov_b64_e32 v[22:23], v[228:229]
	v_mov_b64_e32 v[24:25], v[230:231]
	v_pk_add_f32 v[12:13], v[12:13], v[24:25]
	v_pk_add_f32 v[10:11], v[10:11], v[22:23]
	global_store_dwordx4 v[20:21], v[10:13], off offset:64
	v_cvt_pk_bf16_f32 v16, v10, v11
	v_or_b32_e32 v22, 32, v14
	v_mul_f32_e32 v11, v11, v11
	v_mov_b32_e32 v23, v15
	v_fmac_f32_e32 v11, v10, v10
	v_mul_f32_e32 v10, v13, v13
	v_cvt_pk_bf16_f32 v17, v12, v13
	v_lshl_add_u64 v[22:23], s[12:13], 0, v[22:23]
	v_fmac_f32_e32 v10, v12, v12
	global_store_dwordx2 v[22:23], v[16:17], off
	v_add_f32_e32 v10, v11, v10
	v_add_f32_e32 v16, v26, v10
	s_waitcnt vmcnt(14)
	v_mov_b64_e32 v[10:11], v[232:233]
	v_mov_b64_e32 v[12:13], v[234:235]
	v_pk_add_f32 v[8:9], v[8:9], v[12:13]
	v_pk_add_f32 v[6:7], v[6:7], v[10:11]
	global_store_dwordx4 v[20:21], v[6:9], off offset:512
	v_cvt_pk_bf16_f32 v10, v6, v7
	v_or_b32_e32 v12, 0x100, v14
	v_mul_f32_e32 v7, v7, v7
	v_mov_b32_e32 v13, v15
	v_fmac_f32_e32 v7, v6, v6
	v_mul_f32_e32 v6, v9, v9
	v_cvt_pk_bf16_f32 v11, v8, v9
	v_lshl_add_u64 v[12:13], s[12:13], 0, v[12:13]
	v_fmac_f32_e32 v6, v8, v8
	global_store_dwordx2 v[12:13], v[10:11], off
	v_add_f32_e32 v6, v7, v6
	v_add_f32_e32 v10, v16, v6
	v_or_b32_e32 v14, 0x120, v14
	s_waitcnt vmcnt(15)
	v_mov_b64_e32 v[6:7], v[236:237]
	v_mov_b64_e32 v[8:9], v[238:239]
	v_pk_add_f32 v[4:5], v[4:5], v[8:9]
	v_pk_add_f32 v[2:3], v[2:3], v[6:7]
	global_store_dwordx4 v[20:21], v[2:5], off offset:576
	v_cvt_pk_bf16_f32 v6, v2, v3
	v_cvt_pk_bf16_f32 v7, v4, v5
	v_mul_f32_e32 v3, v3, v3
	v_fmac_f32_e32 v3, v2, v2
	v_mul_f32_e32 v2, v5, v5
	v_fmac_f32_e32 v2, v4, v4
	v_add_f32_e32 v2, v3, v2
	v_add_f32_e32 v2, v10, v2
	ds_bpermute_b32 v3, v162, v2
	v_lshl_add_u64 v[8:9], s[12:13], 0, v[14:15]
	global_store_dwordx2 v[8:9], v[6:7], off
	s_waitcnt lgkmcnt(0)
	v_add_f32_e32 v2, v2, v3
	ds_bpermute_b32 v3, v160, v2
	s_and_saveexec_b64 s[26:27], s[8:9]
	s_cbranch_execz .LBB0_1537
	v_lshlrev_b64 v[4:5], 6, v[18:19]
	v_lshl_add_u64 v[4:5], s[66:67], 0, v[4:5]
	v_lshl_add_u64 v[4:5], s[24:25], 2, v[4:5]
	s_lshl_b32 s68, s43, 2
	v_lshl_add_u64 v[4:5], v[4:5], 0, s[68:69]
	s_waitcnt lgkmcnt(0)
	v_add_f32_e32 v2, v2, v3
	global_store_dword v[4:5], v2, off

.LBB0_1681:
	v_and_b32_e32 v140, 64, v197
	v_xor_b32_e32 v139, 16, v197
	v_add_u32_e32 v140, 64, v140
	v_cmp_lt_i32_e32 vcc, v139, v140
	v_lshl_add_u32 v138, s46, 8, v142
	v_lshl_or_b32 v136, s45, 8, v144
	v_cndmask_b32_e32 v139, v197, v139, vcc
	v_lshlrev_b32_e32 v162, 2, v139
	v_xor_b32_e32 v139, 32, v197
	v_cmp_lt_i32_e32 vcc, v139, v140
	v_ashrrev_i32_e32 v137, 31, v136
	s_lshl_b32 s20, s45, 2
	v_cndmask_b32_e32 v139, v197, v139, vcc
	v_lshlrev_b32_e32 v160, 2, v139
	v_ashrrev_i32_e32 v139, 31, v138
	v_lshlrev_b64 v[140:141], 10, v[138:139]
	v_lshl_add_u64 v[168:169], v[140:141], 0, v[136:137]
	v_lshl_add_u64 v[140:141], v[168:169], 2, s[10:11]
	v_mov_b64_e32 v[204:205], v[140:141]
	global_load_dwordx4 v[208:211], v[204:205], off
	global_load_dwordx4 v[212:215], v[204:205], off offset:64
	global_load_dwordx4 v[216:219], v[204:205], off offset:512
	global_load_dwordx4 v[220:223], v[204:205], off offset:576
	s_mov_b64 s[22:23], 0x10000
	v_lshl_add_u64 v[206:207], v[204:205], 0, s[22:23]
	global_load_dwordx4 v[224:227], v[206:207], off
	global_load_dwordx4 v[228:231], v[206:207], off offset:64
	global_load_dwordx4 v[232:235], v[206:207], off offset:512
	global_load_dwordx4 v[236:239], v[206:207], off offset:576
	s_ashr_i32 s21, s20, 31
	s_waitcnt vmcnt(7)
	v_mov_b64_e32 v[164:165], v[208:209]
	v_mov_b64_e32 v[166:167], v[210:211]
	v_pk_fma_f32 v[166:167], v[128:129], 0.5, v[166:167] op_sel_hi:[1,0,1]
	v_pk_fma_f32 v[164:165], v[126:127], 0.5, v[164:165] op_sel_hi:[1,0,1]
	v_lshlrev_b64 v[126:127], 1, v[168:169]
	v_cvt_pk_bf16_f32 v128, v164, v165
	v_cvt_pk_bf16_f32 v129, v166, v167
	v_lshl_add_u64 v[168:169], s[14:15], 0, v[126:127]
	global_store_dwordx4 v[140:141], v[164:167], off
	global_store_dwordx2 v[168:169], v[128:129], off
	v_mul_f32_e32 v128, v165, v165
	v_mul_f32_e32 v129, v167, v167
	v_fmac_f32_e32 v128, v164, v164
	v_fmac_f32_e32 v129, v166, v166
	v_add_f32_e32 v163, v128, v129
	s_waitcnt vmcnt(8)
	v_mov_b64_e32 v[164:165], v[212:213]
	v_mov_b64_e32 v[166:167], v[214:215]
	v_pk_fma_f32 v[124:125], v[124:125], 0.5, v[166:167] op_sel_hi:[1,0,1]
	v_pk_fma_f32 v[122:123], v[122:123], 0.5, v[164:165] op_sel_hi:[1,0,1]
	global_store_dwordx4 v[140:141], v[122:125], off offset:64
	v_cvt_pk_bf16_f32 v128, v122, v123
	v_or_b32_e32 v164, 32, v126
	v_mul_f32_e32 v123, v123, v123
	v_mov_b32_e32 v165, v127
	v_fmac_f32_e32 v123, v122, v122
	v_mul_f32_e32 v122, v125, v125
	v_cvt_pk_bf16_f32 v129, v124, v125
	v_lshl_add_u64 v[164:165], s[14:15], 0, v[164:165]
	v_fmac_f32_e32 v122, v124, v124
	global_store_dwordx2 v[164:165], v[128:129], off
	v_add_f32_e32 v122, v123, v122
	v_add_f32_e32 v128, v163, v122
	s_waitcnt vmcnt(9)
	v_mov_b64_e32 v[122:123], v[216:217]
	v_mov_b64_e32 v[124:125], v[218:219]
	v_pk_fma_f32 v[120:121], v[120:121], 0.5, v[124:125] op_sel_hi:[1,0,1]
	v_pk_fma_f32 v[118:119], v[118:119], 0.5, v[122:123] op_sel_hi:[1,0,1]
	global_store_dwordx4 v[140:141], v[118:121], off offset:512
	v_cvt_pk_bf16_f32 v122, v118, v119
	v_or_b32_e32 v124, 0x100, v126
	v_mul_f32_e32 v119, v119, v119
	v_mov_b32_e32 v125, v127
	v_fmac_f32_e32 v119, v118, v118
	v_mul_f32_e32 v118, v121, v121
	v_cvt_pk_bf16_f32 v123, v120, v121
	v_lshl_add_u64 v[124:125], s[14:15], 0, v[124:125]
	v_fmac_f32_e32 v118, v120, v120
	global_store_dwordx2 v[124:125], v[122:123], off
	v_add_f32_e32 v118, v119, v118
	v_add_f32_e32 v122, v128, v118
	v_or_b32_e32 v126, 0x120, v126
	s_waitcnt vmcnt(10)
	v_mov_b64_e32 v[118:119], v[220:221]
	v_mov_b64_e32 v[120:121], v[222:223]
	v_pk_fma_f32 v[116:117], v[116:117], 0.5, v[120:121] op_sel_hi:[1,0,1]
	v_pk_fma_f32 v[114:115], v[114:115], 0.5, v[118:119] op_sel_hi:[1,0,1]
	global_store_dwordx4 v[140:141], v[114:117], off offset:576
	v_cvt_pk_bf16_f32 v118, v114, v115
	v_cvt_pk_bf16_f32 v119, v116, v117
	v_mul_f32_e32 v115, v115, v115
	v_fmac_f32_e32 v115, v114, v114
	v_mul_f32_e32 v114, v117, v117
	v_fmac_f32_e32 v114, v116, v116
	v_add_f32_e32 v114, v115, v114
	v_add_f32_e32 v114, v122, v114
	ds_bpermute_b32 v115, v162, v114
	v_lshl_add_u64 v[120:121], s[14:15], 0, v[126:127]
	global_store_dwordx2 v[120:121], v[118:119], off
	s_waitcnt lgkmcnt(0)
	v_add_f32_e32 v114, v114, v115
	ds_bpermute_b32 v115, v160, v114
	s_and_saveexec_b64 s[22:23], s[4:5]
	s_cbranch_execz .LBB0_1683
	v_lshlrev_b64 v[116:117], 6, v[138:139]
	v_lshl_add_u64 v[116:117], s[66:67], 0, v[116:117]
	v_lshl_add_u64 v[116:117], s[20:21], 2, v[116:117]
	s_lshl_b32 s68, s39, 2
	v_lshl_add_u64 v[116:117], v[116:117], 0, s[68:69]
	s_waitcnt lgkmcnt(0)
	v_add_f32_e32 v114, v114, v115
	global_store_dword v[116:117], v114, off
.LBB0_1683:
	s_or_b64 exec, exec, s[22:23]
	v_or_b32_e32 v114, 16, v138
	s_waitcnt lgkmcnt(0)
	v_ashrrev_i32_e32 v115, 31, v114
	v_lshlrev_b64 v[116:117], 10, v[114:115]
	v_lshl_add_u64 v[122:123], v[116:117], 0, v[136:137]
	v_lshl_add_u64 v[116:117], v[122:123], 2, s[10:11]
	s_mov_b64 s[22:23], 0x20000
	v_lshl_add_u64 v[206:207], v[204:205], 0, s[22:23]
	global_load_dwordx4 v[208:211], v[206:207], off
	global_load_dwordx4 v[212:215], v[206:207], off offset:64
	global_load_dwordx4 v[216:219], v[206:207], off offset:512
	global_load_dwordx4 v[220:223], v[206:207], off offset:576
	s_waitcnt vmcnt(16)
	v_mov_b64_e32 v[118:119], v[224:225]
	v_mov_b64_e32 v[120:121], v[226:227]
	v_pk_fma_f32 v[120:121], v[112:113], 0.5, v[120:121] op_sel_hi:[1,0,1]
	v_pk_fma_f32 v[118:119], v[110:111], 0.5, v[118:119] op_sel_hi:[1,0,1]
	v_lshlrev_b64 v[110:111], 1, v[122:123]
	v_cvt_pk_bf16_f32 v112, v118, v119
	v_cvt_pk_bf16_f32 v113, v120, v121
	v_lshl_add_u64 v[122:123], s[14:15], 0, v[110:111]
	global_store_dwordx4 v[116:117], v[118:121], off
	global_store_dwordx2 v[122:123], v[112:113], off
	v_mul_f32_e32 v112, v119, v119
	v_mul_f32_e32 v113, v121, v121
	v_fmac_f32_e32 v112, v118, v118
	v_fmac_f32_e32 v113, v120, v120
	v_add_f32_e32 v122, v112, v113
	s_waitcnt vmcnt(17)
	v_mov_b64_e32 v[118:119], v[228:229]
	v_mov_b64_e32 v[120:121], v[230:231]
	v_pk_fma_f32 v[108:109], v[108:109], 0.5, v[120:121] op_sel_hi:[1,0,1]
	v_pk_fma_f32 v[106:107], v[106:107], 0.5, v[118:119] op_sel_hi:[1,0,1]
	global_store_dwordx4 v[116:117], v[106:109], off offset:64
	v_cvt_pk_bf16_f32 v112, v106, v107
	v_or_b32_e32 v118, 32, v110
	v_mul_f32_e32 v107, v107, v107
	v_mov_b32_e32 v119, v111
	v_fmac_f32_e32 v107, v106, v106
	v_mul_f32_e32 v106, v109, v109
	v_cvt_pk_bf16_f32 v113, v108, v109
	v_lshl_add_u64 v[118:119], s[14:15], 0, v[118:119]
	v_fmac_f32_e32 v106, v108, v108
	global_store_dwordx2 v[118:119], v[112:113], off
	v_add_f32_e32 v106, v107, v106
	v_add_f32_e32 v112, v122, v106
	s_waitcnt vmcnt(18)
	v_mov_b64_e32 v[106:107], v[232:233]
	v_mov_b64_e32 v[108:109], v[234:235]
	v_pk_fma_f32 v[104:105], v[104:105], 0.5, v[108:109] op_sel_hi:[1,0,1]
	v_pk_fma_f32 v[102:103], v[102:103], 0.5, v[106:107] op_sel_hi:[1,0,1]
	global_store_dwordx4 v[116:117], v[102:105], off offset:512
	v_cvt_pk_bf16_f32 v106, v102, v103
	v_or_b32_e32 v108, 0x100, v110
	v_mul_f32_e32 v103, v103, v103
	v_mov_b32_e32 v109, v111
	v_fmac_f32_e32 v103, v102, v102
	v_mul_f32_e32 v102, v105, v105
	v_cvt_pk_bf16_f32 v107, v104, v105
	v_lshl_add_u64 v[108:109], s[14:15], 0, v[108:109]
	v_fmac_f32_e32 v102, v104, v104
	global_store_dwordx2 v[108:109], v[106:107], off
	v_add_f32_e32 v102, v103, v102
	v_add_f32_e32 v106, v112, v102
	v_or_b32_e32 v110, 0x120, v110
	s_waitcnt vmcnt(19)
	v_mov_b64_e32 v[102:103], v[236:237]
	v_mov_b64_e32 v[104:105], v[238:239]
	v_pk_fma_f32 v[100:101], v[100:101], 0.5, v[104:105] op_sel_hi:[1,0,1]
	v_pk_fma_f32 v[98:99], v[98:99], 0.5, v[102:103] op_sel_hi:[1,0,1]
	global_store_dwordx4 v[116:117], v[98:101], off offset:576
	v_cvt_pk_bf16_f32 v102, v98, v99
	v_cvt_pk_bf16_f32 v103, v100, v101
	v_mul_f32_e32 v99, v99, v99
	v_fmac_f32_e32 v99, v98, v98
	v_mul_f32_e32 v98, v101, v101
	v_fmac_f32_e32 v98, v100, v100
	v_add_f32_e32 v98, v99, v98
	v_add_f32_e32 v98, v106, v98
	ds_bpermute_b32 v99, v162, v98
	v_lshl_add_u64 v[104:105], s[14:15], 0, v[110:111]
	global_store_dwordx2 v[104:105], v[102:103], off
	s_waitcnt lgkmcnt(0)
	v_add_f32_e32 v98, v98, v99
	ds_bpermute_b32 v99, v160, v98
	s_and_saveexec_b64 s[22:23], s[4:5]
	s_cbranch_execz .LBB0_1685
	v_lshlrev_b64 v[100:101], 6, v[114:115]
	v_lshl_add_u64 v[100:101], s[66:67], 0, v[100:101]
	v_lshl_add_u64 v[100:101], s[20:21], 2, v[100:101]
	s_lshl_b32 s68, s39, 2
	v_lshl_add_u64 v[100:101], v[100:101], 0, s[68:69]
	s_waitcnt lgkmcnt(0)
	v_add_f32_e32 v98, v98, v99
	global_store_dword v[100:101], v98, off
.LBB0_1685:
	s_or_b64 exec, exec, s[22:23]
	v_or_b32_e32 v98, 32, v138
	s_waitcnt lgkmcnt(0)
	v_ashrrev_i32_e32 v99, 31, v98
	v_lshlrev_b64 v[100:101], 10, v[98:99]
	v_lshl_add_u64 v[106:107], v[100:101], 0, v[136:137]
	v_lshl_add_u64 v[100:101], v[106:107], 2, s[10:11]
	s_mov_b64 s[22:23], 0x30000
	v_lshl_add_u64 v[206:207], v[204:205], 0, s[22:23]
	global_load_dwordx4 v[224:227], v[206:207], off
	global_load_dwordx4 v[228:231], v[206:207], off offset:64
	global_load_dwordx4 v[232:235], v[206:207], off offset:512
	global_load_dwordx4 v[236:239], v[206:207], off offset:576
	s_waitcnt vmcnt(16)
	v_mov_b64_e32 v[102:103], v[208:209]
	v_mov_b64_e32 v[104:105], v[210:211]
	v_pk_fma_f32 v[104:105], v[96:97], 0.5, v[104:105] op_sel_hi:[1,0,1]
	v_pk_fma_f32 v[102:103], v[94:95], 0.5, v[102:103] op_sel_hi:[1,0,1]
	v_lshlrev_b64 v[94:95], 1, v[106:107]
	v_cvt_pk_bf16_f32 v96, v102, v103
	v_cvt_pk_bf16_f32 v97, v104, v105
	v_lshl_add_u64 v[106:107], s[14:15], 0, v[94:95]
	global_store_dwordx4 v[100:101], v[102:105], off
	global_store_dwordx2 v[106:107], v[96:97], off
	v_mul_f32_e32 v96, v103, v103
	v_mul_f32_e32 v97, v105, v105
	v_fmac_f32_e32 v96, v102, v102
	v_fmac_f32_e32 v97, v104, v104
	v_add_f32_e32 v106, v96, v97
	s_waitcnt vmcnt(17)
	v_mov_b64_e32 v[102:103], v[212:213]
	v_mov_b64_e32 v[104:105], v[214:215]
	v_pk_fma_f32 v[92:93], v[92:93], 0.5, v[104:105] op_sel_hi:[1,0,1]
	v_pk_fma_f32 v[90:91], v[90:91], 0.5, v[102:103] op_sel_hi:[1,0,1]
	global_store_dwordx4 v[100:101], v[90:93], off offset:64
	v_cvt_pk_bf16_f32 v96, v90, v91
	v_or_b32_e32 v102, 32, v94
	v_mul_f32_e32 v91, v91, v91
	v_mov_b32_e32 v103, v95
	v_fmac_f32_e32 v91, v90, v90
	v_mul_f32_e32 v90, v93, v93
	v_cvt_pk_bf16_f32 v97, v92, v93
	v_lshl_add_u64 v[102:103], s[14:15], 0, v[102:103]
	v_fmac_f32_e32 v90, v92, v92
	global_store_dwordx2 v[102:103], v[96:97], off
	v_add_f32_e32 v90, v91, v90
	v_add_f32_e32 v96, v106, v90
	s_waitcnt vmcnt(18)
	v_mov_b64_e32 v[90:91], v[216:217]
	v_mov_b64_e32 v[92:93], v[218:219]
	v_pk_fma_f32 v[88:89], v[88:89], 0.5, v[92:93] op_sel_hi:[1,0,1]
	v_pk_fma_f32 v[86:87], v[86:87], 0.5, v[90:91] op_sel_hi:[1,0,1]
	global_store_dwordx4 v[100:101], v[86:89], off offset:512
	v_cvt_pk_bf16_f32 v90, v86, v87
	v_or_b32_e32 v92, 0x100, v94
	v_mul_f32_e32 v87, v87, v87
	v_mov_b32_e32 v93, v95
	v_fmac_f32_e32 v87, v86, v86
	v_mul_f32_e32 v86, v89, v89
	v_cvt_pk_bf16_f32 v91, v88, v89
	v_lshl_add_u64 v[92:93], s[14:15], 0, v[92:93]
	v_fmac_f32_e32 v86, v88, v88
	global_store_dwordx2 v[92:93], v[90:91], off
	v_add_f32_e32 v86, v87, v86
	v_add_f32_e32 v90, v96, v86
	v_or_b32_e32 v94, 0x120, v94
	s_waitcnt vmcnt(19)
	v_mov_b64_e32 v[86:87], v[220:221]
	v_mov_b64_e32 v[88:89], v[222:223]
	v_pk_fma_f32 v[84:85], v[84:85], 0.5, v[88:89] op_sel_hi:[1,0,1]
	v_pk_fma_f32 v[82:83], v[82:83], 0.5, v[86:87] op_sel_hi:[1,0,1]
	global_store_dwordx4 v[100:101], v[82:85], off offset:576
	v_cvt_pk_bf16_f32 v86, v82, v83
	v_cvt_pk_bf16_f32 v87, v84, v85
	v_mul_f32_e32 v83, v83, v83
	v_fmac_f32_e32 v83, v82, v82
	v_mul_f32_e32 v82, v85, v85
	v_fmac_f32_e32 v82, v84, v84
	v_add_f32_e32 v82, v83, v82
	v_add_f32_e32 v82, v90, v82
	ds_bpermute_b32 v83, v162, v82
	v_lshl_add_u64 v[88:89], s[14:15], 0, v[94:95]
	global_store_dwordx2 v[88:89], v[86:87], off
	s_waitcnt lgkmcnt(0)
	v_add_f32_e32 v82, v82, v83
	ds_bpermute_b32 v83, v160, v82
	s_and_saveexec_b64 s[22:23], s[4:5]
	s_cbranch_execz .LBB0_1687
	v_lshlrev_b64 v[84:85], 6, v[98:99]
	v_lshl_add_u64 v[84:85], s[66:67], 0, v[84:85]
	v_lshl_add_u64 v[84:85], s[20:21], 2, v[84:85]
	s_lshl_b32 s68, s39, 2
	v_lshl_add_u64 v[84:85], v[84:85], 0, s[68:69]
	s_waitcnt lgkmcnt(0)
	v_add_f32_e32 v82, v82, v83
	global_store_dword v[84:85], v82, off
.LBB0_1687:
	s_or_b64 exec, exec, s[22:23]
	v_or_b32_e32 v82, 48, v138
	s_waitcnt lgkmcnt(0)
	v_ashrrev_i32_e32 v83, 31, v82
	v_lshlrev_b64 v[84:85], 10, v[82:83]
	v_lshl_add_u64 v[90:91], v[84:85], 0, v[136:137]
	v_lshl_add_u64 v[84:85], v[90:91], 2, s[10:11]
	s_mov_b64 s[22:23], 0x80000
	v_lshl_add_u64 v[206:207], v[204:205], 0, s[22:23]
	global_load_dwordx4 v[208:211], v[206:207], off
	global_load_dwordx4 v[212:215], v[206:207], off offset:64
	global_load_dwordx4 v[216:219], v[206:207], off offset:512
	global_load_dwordx4 v[220:223], v[206:207], off offset:576
	s_waitcnt vmcnt(16)
	v_mov_b64_e32 v[86:87], v[224:225]
	v_mov_b64_e32 v[88:89], v[226:227]
	v_pk_fma_f32 v[88:89], v[80:81], 0.5, v[88:89] op_sel_hi:[1,0,1]
	v_pk_fma_f32 v[86:87], v[78:79], 0.5, v[86:87] op_sel_hi:[1,0,1]
	v_lshlrev_b64 v[78:79], 1, v[90:91]
	v_cvt_pk_bf16_f32 v80, v86, v87
	v_cvt_pk_bf16_f32 v81, v88, v89
	v_lshl_add_u64 v[90:91], s[14:15], 0, v[78:79]
	global_store_dwordx4 v[84:85], v[86:89], off
	global_store_dwordx2 v[90:91], v[80:81], off
	v_mul_f32_e32 v80, v87, v87
	v_mul_f32_e32 v81, v89, v89
	v_fmac_f32_e32 v80, v86, v86
	v_fmac_f32_e32 v81, v88, v88
	v_add_f32_e32 v90, v80, v81
	s_waitcnt vmcnt(17)
	v_mov_b64_e32 v[86:87], v[228:229]
	v_mov_b64_e32 v[88:89], v[230:231]
	v_pk_fma_f32 v[76:77], v[76:77], 0.5, v[88:89] op_sel_hi:[1,0,1]
	v_pk_fma_f32 v[74:75], v[74:75], 0.5, v[86:87] op_sel_hi:[1,0,1]
	global_store_dwordx4 v[84:85], v[74:77], off offset:64
	v_cvt_pk_bf16_f32 v80, v74, v75
	v_or_b32_e32 v86, 32, v78
	v_mul_f32_e32 v75, v75, v75
	v_mov_b32_e32 v87, v79
	v_fmac_f32_e32 v75, v74, v74
	v_mul_f32_e32 v74, v77, v77
	v_cvt_pk_bf16_f32 v81, v76, v77
	v_lshl_add_u64 v[86:87], s[14:15], 0, v[86:87]
	v_fmac_f32_e32 v74, v76, v76
	global_store_dwordx2 v[86:87], v[80:81], off
	v_add_f32_e32 v74, v75, v74
	v_add_f32_e32 v80, v90, v74
	s_waitcnt vmcnt(18)
	v_mov_b64_e32 v[74:75], v[232:233]
	v_mov_b64_e32 v[76:77], v[234:235]
	v_pk_fma_f32 v[72:73], v[72:73], 0.5, v[76:77] op_sel_hi:[1,0,1]
	v_pk_fma_f32 v[70:71], v[70:71], 0.5, v[74:75] op_sel_hi:[1,0,1]
	global_store_dwordx4 v[84:85], v[70:73], off offset:512
	v_cvt_pk_bf16_f32 v74, v70, v71
	v_or_b32_e32 v76, 0x100, v78
	v_mul_f32_e32 v71, v71, v71
	v_mov_b32_e32 v77, v79
	v_fmac_f32_e32 v71, v70, v70
	v_mul_f32_e32 v70, v73, v73
	v_cvt_pk_bf16_f32 v75, v72, v73
	v_lshl_add_u64 v[76:77], s[14:15], 0, v[76:77]
	v_fmac_f32_e32 v70, v72, v72
	global_store_dwordx2 v[76:77], v[74:75], off
	v_add_f32_e32 v70, v71, v70
	v_add_f32_e32 v74, v80, v70
	v_or_b32_e32 v78, 0x120, v78
	s_waitcnt vmcnt(19)
	v_mov_b64_e32 v[70:71], v[236:237]
	v_mov_b64_e32 v[72:73], v[238:239]
	v_pk_fma_f32 v[68:69], v[68:69], 0.5, v[72:73] op_sel_hi:[1,0,1]
	v_pk_fma_f32 v[66:67], v[66:67], 0.5, v[70:71] op_sel_hi:[1,0,1]
	global_store_dwordx4 v[84:85], v[66:69], off offset:576
	v_cvt_pk_bf16_f32 v70, v66, v67
	v_cvt_pk_bf16_f32 v71, v68, v69
	v_mul_f32_e32 v67, v67, v67
	v_fmac_f32_e32 v67, v66, v66
	v_mul_f32_e32 v66, v69, v69
	v_fmac_f32_e32 v66, v68, v68
	v_add_f32_e32 v66, v67, v66
	v_add_f32_e32 v66, v74, v66
	ds_bpermute_b32 v67, v162, v66
	v_lshl_add_u64 v[72:73], s[14:15], 0, v[78:79]
	global_store_dwordx2 v[72:73], v[70:71], off
	s_waitcnt lgkmcnt(0)
	v_add_f32_e32 v66, v66, v67
	ds_bpermute_b32 v67, v160, v66
	s_and_saveexec_b64 s[22:23], s[4:5]
	s_cbranch_execz .LBB0_1689
	v_lshlrev_b64 v[68:69], 6, v[82:83]
	v_lshl_add_u64 v[68:69], s[66:67], 0, v[68:69]
	v_lshl_add_u64 v[68:69], s[20:21], 2, v[68:69]
	s_lshl_b32 s68, s39, 2
	v_lshl_add_u64 v[68:69], v[68:69], 0, s[68:69]
	s_waitcnt lgkmcnt(0)
	v_add_f32_e32 v66, v66, v67
	global_store_dword v[68:69], v66, off
.LBB0_1689:
	s_or_b64 exec, exec, s[22:23]
	v_add_u32_e32 v66, 0x80, v138
	s_waitcnt lgkmcnt(0)
	v_ashrrev_i32_e32 v67, 31, v66
	v_lshlrev_b64 v[68:69], 10, v[66:67]
	v_lshl_add_u64 v[74:75], v[68:69], 0, v[136:137]
	v_lshl_add_u64 v[68:69], v[74:75], 2, s[10:11]
	s_mov_b64 s[22:23], 0x90000
	v_lshl_add_u64 v[206:207], v[204:205], 0, s[22:23]
	global_load_dwordx4 v[224:227], v[206:207], off
	global_load_dwordx4 v[228:231], v[206:207], off offset:64
	global_load_dwordx4 v[232:235], v[206:207], off offset:512
	global_load_dwordx4 v[236:239], v[206:207], off offset:576
	s_waitcnt vmcnt(16)
	v_mov_b64_e32 v[70:71], v[208:209]
	v_mov_b64_e32 v[72:73], v[210:211]
	v_pk_fma_f32 v[72:73], v[64:65], 0.5, v[72:73] op_sel_hi:[1,0,1]
	v_pk_fma_f32 v[70:71], v[62:63], 0.5, v[70:71] op_sel_hi:[1,0,1]
	v_lshlrev_b64 v[62:63], 1, v[74:75]
	v_cvt_pk_bf16_f32 v64, v70, v71
	v_cvt_pk_bf16_f32 v65, v72, v73
	v_lshl_add_u64 v[74:75], s[14:15], 0, v[62:63]
	global_store_dwordx4 v[68:69], v[70:73], off
	global_store_dwordx2 v[74:75], v[64:65], off
	v_mul_f32_e32 v64, v71, v71
	v_mul_f32_e32 v65, v73, v73
	v_fmac_f32_e32 v64, v70, v70
	v_fmac_f32_e32 v65, v72, v72
	v_add_f32_e32 v74, v64, v65
	s_waitcnt vmcnt(17)
	v_mov_b64_e32 v[70:71], v[212:213]
	v_mov_b64_e32 v[72:73], v[214:215]
	v_pk_fma_f32 v[60:61], v[60:61], 0.5, v[72:73] op_sel_hi:[1,0,1]
	v_pk_fma_f32 v[58:59], v[58:59], 0.5, v[70:71] op_sel_hi:[1,0,1]
	global_store_dwordx4 v[68:69], v[58:61], off offset:64
	v_cvt_pk_bf16_f32 v64, v58, v59
	v_or_b32_e32 v70, 32, v62
	v_mul_f32_e32 v59, v59, v59
	v_mov_b32_e32 v71, v63
	v_fmac_f32_e32 v59, v58, v58
	v_mul_f32_e32 v58, v61, v61
	v_cvt_pk_bf16_f32 v65, v60, v61
	v_lshl_add_u64 v[70:71], s[14:15], 0, v[70:71]
	v_fmac_f32_e32 v58, v60, v60
	global_store_dwordx2 v[70:71], v[64:65], off
	v_add_f32_e32 v58, v59, v58
	v_add_f32_e32 v64, v74, v58
	s_waitcnt vmcnt(18)
	v_mov_b64_e32 v[58:59], v[216:217]
	v_mov_b64_e32 v[60:61], v[218:219]
	v_pk_fma_f32 v[56:57], v[56:57], 0.5, v[60:61] op_sel_hi:[1,0,1]
	v_pk_fma_f32 v[54:55], v[54:55], 0.5, v[58:59] op_sel_hi:[1,0,1]
	global_store_dwordx4 v[68:69], v[54:57], off offset:512
	v_cvt_pk_bf16_f32 v58, v54, v55
	v_or_b32_e32 v60, 0x100, v62
	v_mul_f32_e32 v55, v55, v55
	v_mov_b32_e32 v61, v63
	v_fmac_f32_e32 v55, v54, v54
	v_mul_f32_e32 v54, v57, v57
	v_cvt_pk_bf16_f32 v59, v56, v57
	v_lshl_add_u64 v[60:61], s[14:15], 0, v[60:61]
	v_fmac_f32_e32 v54, v56, v56
	global_store_dwordx2 v[60:61], v[58:59], off
	v_add_f32_e32 v54, v55, v54
	v_add_f32_e32 v58, v64, v54
	v_or_b32_e32 v62, 0x120, v62
	s_waitcnt vmcnt(19)
	v_mov_b64_e32 v[54:55], v[220:221]
	v_mov_b64_e32 v[56:57], v[222:223]
	v_pk_fma_f32 v[52:53], v[52:53], 0.5, v[56:57] op_sel_hi:[1,0,1]
	v_pk_fma_f32 v[50:51], v[50:51], 0.5, v[54:55] op_sel_hi:[1,0,1]
	global_store_dwordx4 v[68:69], v[50:53], off offset:576
	v_cvt_pk_bf16_f32 v54, v50, v51
	v_cvt_pk_bf16_f32 v55, v52, v53
	v_mul_f32_e32 v51, v51, v51
	v_fmac_f32_e32 v51, v50, v50
	v_mul_f32_e32 v50, v53, v53
	v_fmac_f32_e32 v50, v52, v52
	v_add_f32_e32 v50, v51, v50
	v_add_f32_e32 v50, v58, v50
	ds_bpermute_b32 v51, v162, v50
	v_lshl_add_u64 v[56:57], s[14:15], 0, v[62:63]
	global_store_dwordx2 v[56:57], v[54:55], off
	s_waitcnt lgkmcnt(0)
	v_add_f32_e32 v50, v50, v51
	ds_bpermute_b32 v51, v160, v50
	s_and_saveexec_b64 s[22:23], s[4:5]
	s_cbranch_execz .LBB0_1691
	v_lshlrev_b64 v[52:53], 6, v[66:67]
	v_lshl_add_u64 v[52:53], s[66:67], 0, v[52:53]
	v_lshl_add_u64 v[52:53], s[20:21], 2, v[52:53]
	s_lshl_b32 s68, s39, 2
	v_lshl_add_u64 v[52:53], v[52:53], 0, s[68:69]
	s_waitcnt lgkmcnt(0)
	v_add_f32_e32 v50, v50, v51
	global_store_dword v[52:53], v50, off
.LBB0_1691:
	s_or_b64 exec, exec, s[22:23]
	v_add_u32_e32 v50, 0x90, v138
	s_waitcnt lgkmcnt(0)
	v_ashrrev_i32_e32 v51, 31, v50
	v_lshlrev_b64 v[52:53], 10, v[50:51]
	v_lshl_add_u64 v[58:59], v[52:53], 0, v[136:137]
	v_lshl_add_u64 v[52:53], v[58:59], 2, s[10:11]
	s_mov_b64 s[22:23], 0xa0000
	v_lshl_add_u64 v[206:207], v[204:205], 0, s[22:23]
	global_load_dwordx4 v[208:211], v[206:207], off
	global_load_dwordx4 v[212:215], v[206:207], off offset:64
	global_load_dwordx4 v[216:219], v[206:207], off offset:512
	global_load_dwordx4 v[220:223], v[206:207], off offset:576
	s_waitcnt vmcnt(16)
	v_mov_b64_e32 v[54:55], v[224:225]
	v_mov_b64_e32 v[56:57], v[226:227]
	v_pk_fma_f32 v[56:57], v[48:49], 0.5, v[56:57] op_sel_hi:[1,0,1]
	v_pk_fma_f32 v[54:55], v[46:47], 0.5, v[54:55] op_sel_hi:[1,0,1]
	v_lshlrev_b64 v[46:47], 1, v[58:59]
	v_cvt_pk_bf16_f32 v48, v54, v55
	v_cvt_pk_bf16_f32 v49, v56, v57
	v_lshl_add_u64 v[58:59], s[14:15], 0, v[46:47]
	global_store_dwordx4 v[52:53], v[54:57], off
	global_store_dwordx2 v[58:59], v[48:49], off
	v_mul_f32_e32 v48, v55, v55
	v_mul_f32_e32 v49, v57, v57
	v_fmac_f32_e32 v48, v54, v54
	v_fmac_f32_e32 v49, v56, v56
	v_add_f32_e32 v58, v48, v49
	s_waitcnt vmcnt(17)
	v_mov_b64_e32 v[54:55], v[228:229]
	v_mov_b64_e32 v[56:57], v[230:231]
	v_pk_fma_f32 v[44:45], v[44:45], 0.5, v[56:57] op_sel_hi:[1,0,1]
	v_pk_fma_f32 v[42:43], v[42:43], 0.5, v[54:55] op_sel_hi:[1,0,1]
	global_store_dwordx4 v[52:53], v[42:45], off offset:64
	v_cvt_pk_bf16_f32 v48, v42, v43
	v_or_b32_e32 v54, 32, v46
	v_mul_f32_e32 v43, v43, v43
	v_mov_b32_e32 v55, v47
	v_fmac_f32_e32 v43, v42, v42
	v_mul_f32_e32 v42, v45, v45
	v_cvt_pk_bf16_f32 v49, v44, v45
	v_lshl_add_u64 v[54:55], s[14:15], 0, v[54:55]
	v_fmac_f32_e32 v42, v44, v44
	global_store_dwordx2 v[54:55], v[48:49], off
	v_add_f32_e32 v42, v43, v42
	v_add_f32_e32 v48, v58, v42
	s_waitcnt vmcnt(18)
	v_mov_b64_e32 v[42:43], v[232:233]
	v_mov_b64_e32 v[44:45], v[234:235]
	v_pk_fma_f32 v[40:41], v[40:41], 0.5, v[44:45] op_sel_hi:[1,0,1]
	v_pk_fma_f32 v[38:39], v[38:39], 0.5, v[42:43] op_sel_hi:[1,0,1]
	global_store_dwordx4 v[52:53], v[38:41], off offset:512
	v_cvt_pk_bf16_f32 v42, v38, v39
	v_or_b32_e32 v44, 0x100, v46
	v_mul_f32_e32 v39, v39, v39
	v_mov_b32_e32 v45, v47
	v_fmac_f32_e32 v39, v38, v38
	v_mul_f32_e32 v38, v41, v41
	v_cvt_pk_bf16_f32 v43, v40, v41
	v_lshl_add_u64 v[44:45], s[14:15], 0, v[44:45]
	v_fmac_f32_e32 v38, v40, v40
	global_store_dwordx2 v[44:45], v[42:43], off
	v_add_f32_e32 v38, v39, v38
	v_add_f32_e32 v42, v48, v38
	v_or_b32_e32 v46, 0x120, v46
	s_waitcnt vmcnt(19)
	v_mov_b64_e32 v[38:39], v[236:237]
	v_mov_b64_e32 v[40:41], v[238:239]
	v_pk_fma_f32 v[36:37], v[36:37], 0.5, v[40:41] op_sel_hi:[1,0,1]
	v_pk_fma_f32 v[34:35], v[34:35], 0.5, v[38:39] op_sel_hi:[1,0,1]
	global_store_dwordx4 v[52:53], v[34:37], off offset:576
	v_cvt_pk_bf16_f32 v38, v34, v35
	v_cvt_pk_bf16_f32 v39, v36, v37
	v_mul_f32_e32 v35, v35, v35
	v_fmac_f32_e32 v35, v34, v34
	v_mul_f32_e32 v34, v37, v37
	v_fmac_f32_e32 v34, v36, v36
	v_add_f32_e32 v34, v35, v34
	v_add_f32_e32 v34, v42, v34
	ds_bpermute_b32 v35, v162, v34
	v_lshl_add_u64 v[40:41], s[14:15], 0, v[46:47]
	global_store_dwordx2 v[40:41], v[38:39], off
	s_waitcnt lgkmcnt(0)
	v_add_f32_e32 v34, v34, v35
	ds_bpermute_b32 v35, v160, v34
	s_and_saveexec_b64 s[22:23], s[4:5]
	s_cbranch_execz .LBB0_1693
	v_lshlrev_b64 v[36:37], 6, v[50:51]
	v_lshl_add_u64 v[36:37], s[66:67], 0, v[36:37]
	v_lshl_add_u64 v[36:37], s[20:21], 2, v[36:37]
	s_lshl_b32 s68, s39, 2
	v_lshl_add_u64 v[36:37], v[36:37], 0, s[68:69]
	s_waitcnt lgkmcnt(0)
	v_add_f32_e32 v34, v34, v35
	global_store_dword v[36:37], v34, off
.LBB0_1693:
	s_or_b64 exec, exec, s[22:23]
	v_add_u32_e32 v34, 0xa0, v138
	s_waitcnt lgkmcnt(0)
	v_ashrrev_i32_e32 v35, 31, v34
	v_lshlrev_b64 v[36:37], 10, v[34:35]
	v_lshl_add_u64 v[42:43], v[36:37], 0, v[136:137]
	v_lshl_add_u64 v[36:37], v[42:43], 2, s[10:11]
	s_mov_b64 s[22:23], 0xb0000
	v_lshl_add_u64 v[206:207], v[204:205], 0, s[22:23]
	global_load_dwordx4 v[224:227], v[206:207], off
	global_load_dwordx4 v[228:231], v[206:207], off offset:64
	global_load_dwordx4 v[232:235], v[206:207], off offset:512
	global_load_dwordx4 v[236:239], v[206:207], off offset:576
	s_waitcnt vmcnt(16)
	v_mov_b64_e32 v[38:39], v[208:209]
	v_mov_b64_e32 v[40:41], v[210:211]
	v_pk_fma_f32 v[40:41], v[32:33], 0.5, v[40:41] op_sel_hi:[1,0,1]
	v_pk_fma_f32 v[38:39], v[30:31], 0.5, v[38:39] op_sel_hi:[1,0,1]
	v_lshlrev_b64 v[30:31], 1, v[42:43]
	v_cvt_pk_bf16_f32 v32, v38, v39
	v_cvt_pk_bf16_f32 v33, v40, v41
	v_lshl_add_u64 v[42:43], s[14:15], 0, v[30:31]
	global_store_dwordx4 v[36:37], v[38:41], off
	global_store_dwordx2 v[42:43], v[32:33], off
	v_mul_f32_e32 v32, v39, v39
	v_mul_f32_e32 v33, v41, v41
	v_fmac_f32_e32 v32, v38, v38
	v_fmac_f32_e32 v33, v40, v40
	v_add_f32_e32 v42, v32, v33
	s_waitcnt vmcnt(17)
	v_mov_b64_e32 v[38:39], v[212:213]
	v_mov_b64_e32 v[40:41], v[214:215]
	v_pk_fma_f32 v[28:29], v[28:29], 0.5, v[40:41] op_sel_hi:[1,0,1]
	v_pk_fma_f32 v[26:27], v[26:27], 0.5, v[38:39] op_sel_hi:[1,0,1]
	global_store_dwordx4 v[36:37], v[26:29], off offset:64
	v_cvt_pk_bf16_f32 v32, v26, v27
	v_or_b32_e32 v38, 32, v30
	v_mul_f32_e32 v27, v27, v27
	v_mov_b32_e32 v39, v31
	v_fmac_f32_e32 v27, v26, v26
	v_mul_f32_e32 v26, v29, v29
	v_cvt_pk_bf16_f32 v33, v28, v29
	v_lshl_add_u64 v[38:39], s[14:15], 0, v[38:39]
	v_fmac_f32_e32 v26, v28, v28
	global_store_dwordx2 v[38:39], v[32:33], off
	v_add_f32_e32 v26, v27, v26
	v_add_f32_e32 v32, v42, v26
	s_waitcnt vmcnt(18)
	v_mov_b64_e32 v[26:27], v[216:217]
	v_mov_b64_e32 v[28:29], v[218:219]
	v_pk_fma_f32 v[24:25], v[24:25], 0.5, v[28:29] op_sel_hi:[1,0,1]
	v_pk_fma_f32 v[22:23], v[22:23], 0.5, v[26:27] op_sel_hi:[1,0,1]
	global_store_dwordx4 v[36:37], v[22:25], off offset:512
	v_cvt_pk_bf16_f32 v26, v22, v23
	v_or_b32_e32 v28, 0x100, v30
	v_mul_f32_e32 v23, v23, v23
	v_mov_b32_e32 v29, v31
	v_fmac_f32_e32 v23, v22, v22
	v_mul_f32_e32 v22, v25, v25
	v_cvt_pk_bf16_f32 v27, v24, v25
	v_lshl_add_u64 v[28:29], s[14:15], 0, v[28:29]
	v_fmac_f32_e32 v22, v24, v24
	global_store_dwordx2 v[28:29], v[26:27], off
	v_add_f32_e32 v22, v23, v22
	v_add_f32_e32 v26, v32, v22
	v_or_b32_e32 v30, 0x120, v30
	s_waitcnt vmcnt(19)
	v_mov_b64_e32 v[22:23], v[220:221]
	v_mov_b64_e32 v[24:25], v[222:223]
	v_pk_fma_f32 v[20:21], v[20:21], 0.5, v[24:25] op_sel_hi:[1,0,1]
	v_pk_fma_f32 v[18:19], v[18:19], 0.5, v[22:23] op_sel_hi:[1,0,1]
	global_store_dwordx4 v[36:37], v[18:21], off offset:576
	v_cvt_pk_bf16_f32 v22, v18, v19
	v_cvt_pk_bf16_f32 v23, v20, v21
	v_mul_f32_e32 v19, v19, v19
	v_fmac_f32_e32 v19, v18, v18
	v_mul_f32_e32 v18, v21, v21
	v_fmac_f32_e32 v18, v20, v20
	v_add_f32_e32 v18, v19, v18
	v_add_f32_e32 v18, v26, v18
	ds_bpermute_b32 v19, v162, v18
	v_lshl_add_u64 v[24:25], s[14:15], 0, v[30:31]
	global_store_dwordx2 v[24:25], v[22:23], off
	s_waitcnt lgkmcnt(0)
	v_add_f32_e32 v18, v18, v19
	ds_bpermute_b32 v19, v160, v18
	s_and_saveexec_b64 s[22:23], s[4:5]
	s_cbranch_execz .LBB0_1695
	v_lshlrev_b64 v[20:21], 6, v[34:35]
	v_lshl_add_u64 v[20:21], s[66:67], 0, v[20:21]
	v_lshl_add_u64 v[20:21], s[20:21], 2, v[20:21]
	s_lshl_b32 s68, s39, 2
	v_lshl_add_u64 v[20:21], v[20:21], 0, s[68:69]
	s_waitcnt lgkmcnt(0)
	v_add_f32_e32 v18, v18, v19
	global_store_dword v[20:21], v18, off
.LBB0_1695:
	s_or_b64 exec, exec, s[22:23]
	v_add_u32_e32 v18, 0xb0, v138
	s_waitcnt lgkmcnt(0)
	v_ashrrev_i32_e32 v19, 31, v18
	v_lshlrev_b64 v[20:21], 10, v[18:19]
	v_lshl_add_u64 v[26:27], v[20:21], 0, v[136:137]
	v_lshl_add_u64 v[20:21], v[26:27], 2, s[10:11]
	s_waitcnt vmcnt(12)
	v_mov_b64_e32 v[22:23], v[224:225]
	v_mov_b64_e32 v[24:25], v[226:227]
	v_pk_fma_f32 v[24:25], v[16:17], 0.5, v[24:25] op_sel_hi:[1,0,1]
	v_pk_fma_f32 v[22:23], v[14:15], 0.5, v[22:23] op_sel_hi:[1,0,1]
	v_lshlrev_b64 v[14:15], 1, v[26:27]
	v_cvt_pk_bf16_f32 v16, v22, v23
	v_cvt_pk_bf16_f32 v17, v24, v25
	v_lshl_add_u64 v[26:27], s[14:15], 0, v[14:15]
	global_store_dwordx4 v[20:21], v[22:25], off
	global_store_dwordx2 v[26:27], v[16:17], off
	v_mul_f32_e32 v16, v23, v23
	v_mul_f32_e32 v17, v25, v25
	v_fmac_f32_e32 v16, v22, v22
	v_fmac_f32_e32 v17, v24, v24
	v_add_f32_e32 v26, v16, v17
	s_waitcnt vmcnt(13)
	v_mov_b64_e32 v[22:23], v[228:229]
	v_mov_b64_e32 v[24:25], v[230:231]
	v_pk_fma_f32 v[12:13], v[12:13], 0.5, v[24:25] op_sel_hi:[1,0,1]
	v_pk_fma_f32 v[10:11], v[10:11], 0.5, v[22:23] op_sel_hi:[1,0,1]
	global_store_dwordx4 v[20:21], v[10:13], off offset:64
	v_cvt_pk_bf16_f32 v16, v10, v11
	v_or_b32_e32 v22, 32, v14
	v_mul_f32_e32 v11, v11, v11
	v_mov_b32_e32 v23, v15
	v_fmac_f32_e32 v11, v10, v10
	v_mul_f32_e32 v10, v13, v13
	v_cvt_pk_bf16_f32 v17, v12, v13
	v_lshl_add_u64 v[22:23], s[14:15], 0, v[22:23]
	v_fmac_f32_e32 v10, v12, v12
	global_store_dwordx2 v[22:23], v[16:17], off
	v_add_f32_e32 v10, v11, v10
	v_add_f32_e32 v16, v26, v10
	s_waitcnt vmcnt(14)
	v_mov_b64_e32 v[10:11], v[232:233]
	v_mov_b64_e32 v[12:13], v[234:235]
	v_pk_fma_f32 v[8:9], v[8:9], 0.5, v[12:13] op_sel_hi:[1,0,1]
	v_pk_fma_f32 v[6:7], v[6:7], 0.5, v[10:11] op_sel_hi:[1,0,1]
	global_store_dwordx4 v[20:21], v[6:9], off offset:512
	v_cvt_pk_bf16_f32 v10, v6, v7
	v_or_b32_e32 v12, 0x100, v14
	v_mul_f32_e32 v7, v7, v7
	v_mov_b32_e32 v13, v15
	v_fmac_f32_e32 v7, v6, v6
	v_mul_f32_e32 v6, v9, v9
	v_cvt_pk_bf16_f32 v11, v8, v9
	v_lshl_add_u64 v[12:13], s[14:15], 0, v[12:13]
	v_fmac_f32_e32 v6, v8, v8
	global_store_dwordx2 v[12:13], v[10:11], off
	v_add_f32_e32 v6, v7, v6
	v_add_f32_e32 v10, v16, v6
	v_or_b32_e32 v14, 0x120, v14
	s_waitcnt vmcnt(15)
	v_mov_b64_e32 v[6:7], v[236:237]
	v_mov_b64_e32 v[8:9], v[238:239]
	v_pk_fma_f32 v[4:5], v[4:5], 0.5, v[8:9] op_sel_hi:[1,0,1]
	v_pk_fma_f32 v[2:3], v[2:3], 0.5, v[6:7] op_sel_hi:[1,0,1]
	global_store_dwordx4 v[20:21], v[2:5], off offset:576
	v_cvt_pk_bf16_f32 v6, v2, v3
	v_cvt_pk_bf16_f32 v7, v4, v5
	v_mul_f32_e32 v3, v3, v3
	v_fmac_f32_e32 v3, v2, v2
	v_mul_f32_e32 v2, v5, v5
	v_fmac_f32_e32 v2, v4, v4
	v_add_f32_e32 v2, v3, v2
	v_add_f32_e32 v2, v10, v2
	ds_bpermute_b32 v3, v162, v2
	v_lshl_add_u64 v[8:9], s[14:15], 0, v[14:15]
	global_store_dwordx2 v[8:9], v[6:7], off
	s_waitcnt lgkmcnt(0)
	v_add_f32_e32 v2, v2, v3
	ds_bpermute_b32 v3, v160, v2
	s_and_saveexec_b64 s[22:23], s[4:5]
	s_cbranch_execz .LBB0_1697
	v_lshlrev_b64 v[4:5], 6, v[18:19]
	v_lshl_add_u64 v[4:5], s[66:67], 0, v[4:5]
	v_lshl_add_u64 v[4:5], s[20:21], 2, v[4:5]
	s_lshl_b32 s68, s39, 2
	v_lshl_add_u64 v[4:5], v[4:5], 0, s[68:69]
	s_waitcnt lgkmcnt(0)
	v_add_f32_e32 v2, v2, v3
	global_store_dword v[4:5], v2, off
